# attention main line: the next step's K-fragment reads moved out of the PV burst (issued after the last PV MFMA) in the two steps that had them inside it
# speedup vs baseline: 1.0058x; 1.0009x over previous
; DI float fexp2(float x) { return __builtin_amdgcn_exp2f(x); }
; DI void phase_attn(const Params& p, int hf, bool skipctx, char* smem, int& rot) {
;     ...
;     auto compute = [&](int buf, int half) {
;       const char* sk = smem + buf * STG + half * 64 * KROW; const char* sv = smem + buf * STG + KB_ + half * 128;
;       f32x16 st[2]; st[0] = zero16(); st[1] = zero16();
;       {
;         bf16x8 kf[2][6];
; #pragma unroll
;         for (int kb = 0; kb < 2; ++kb)
; #pragma unroll
;           for (int ks = 0; ks < 6; ++ks) kf[kb][ks] = *(const bf16x8*)(sk + (kb * 32 + r) * KROW + (ks * 16 + h * 8) * 2);
;         __builtin_amdgcn_sched_barrier(0);
; #pragma unroll
;         for (int ks = 0; ks < 6; ++ks)
; #pragma unroll
;           for (int kb = 0; kb < 2; ++kb) st[kb] = MFMA(kf[kb][ks], qf[ks], st[kb]);
;         __builtin_amdgcn_sched_barrier(0);
;       }
;       bf16x8 vf[2][2][2];
; #pragma unroll
;       for (int kb = 0; kb < 2; ++kb)
; #pragma unroll
;         for (int s2 = 0; s2 < 2; ++s2)
; #pragma unroll
;           for (int dvb = 0; dvb < 2; ++dvb) {
;             const char* vp = sv + (dvb * 32 + r) * VROW + (kb * 32 + 16 * s2 + 4 * h) * 2;
;             const s16x4 lo = *(const s16x4*)vp, hi = *(const s16x4*)(vp + 16);
;             vf[kb][s2][dvb] = __builtin_shufflevector(lo, hi, 0, 1, 2, 3, 4, 5, 6, 7);
;           }
;       float mx = st[0][0];
; #pragma unroll
;       for (int i = 0; i < 16; ++i) { mx = fmaxf(mx, st[0][i]); mx = fmaxf(mx, st[1][i]); }
;       if (__any(mx > m_run + 8.f)) {
;         mx = fmaxf(mx, __shfl_xor(mx, 32));
;         const float m_new = fmaxf(m_run, mx);
;         const float alpha = fexp2(m_run - m_new);
;         m_run = m_new;
;         l_run *= alpha;
; #pragma unroll
;         for (int i = 0; i < 16; ++i) { o[0][i] *= alpha; o[1][i] *= alpha; }
;       }
;       float ps = 0.f;
; #pragma unroll
;       for (int kb = 0; kb < 2; ++kb)
; #pragma unroll
;         for (int i = 0; i < 16; ++i) { const float e = fexp2(st[kb][i] - m_run); st[kb][i] = e; ps += e; }
;       l_run += ps;
; #pragma unroll
;       for (int kb = 0; kb < 2; ++kb)
; #pragma unroll
;         for (int s2 = 0; s2 < 2; ++s2) {
;           const bf16x8 pb = pack8(st[kb][8 * s2 + 0], st[kb][8 * s2 + 1], st[kb][8 * s2 + 2], st[kb][8 * s2 + 3], st[kb][8 * s2 + 4], st[kb][8 * s2 + 5], st[kb][8 * s2 + 6], st[kb][8 * s2 + 7]);
; #pragma unroll
.LBB0_797:
	s_cmp_eq_u32 s101, 0
	s_cbranch_scc1 .Lsc0_fb0e
	s_waitcnt lgkmcnt(11)
	v_mfma_f32_32x32x16_bf16 v[48:63], v[32:35], v[64:67], v[176:191]
	s_waitcnt lgkmcnt(5)
	v_mfma_f32_32x32x16_bf16 v[32:47], v[36:39], v[64:67], v[176:191]
	v_mfma_f32_32x32x16_bf16 v[48:63], v[128:131], v[68:71], v[48:63]
	s_waitcnt lgkmcnt(4)
	v_mfma_f32_32x32x16_bf16 v[32:47], v[148:151], v[68:71], v[32:47]
	v_mfma_f32_32x32x16_bf16 v[48:63], v[132:135], v[72:75], v[48:63]
	s_waitcnt lgkmcnt(3)
	v_mfma_f32_32x32x16_bf16 v[32:47], v[152:155], v[72:75], v[32:47]
	v_mfma_f32_32x32x16_bf16 v[48:63], v[136:139], v[88:91], v[48:63]
	s_waitcnt lgkmcnt(2)
	v_mfma_f32_32x32x16_bf16 v[32:47], v[156:159], v[88:91], v[32:47]
	v_mfma_f32_32x32x16_bf16 v[48:63], v[140:143], v[96:99], v[48:63]
	s_waitcnt lgkmcnt(1)
	v_mfma_f32_32x32x16_bf16 v[32:47], v[214:217], v[96:99], v[32:47]
	v_mfma_f32_32x32x16_bf16 v[48:63], v[144:147], v[100:103], v[48:63]
	s_waitcnt lgkmcnt(0)
	v_mfma_f32_32x32x16_bf16 v[32:47], v[234:237], v[100:103], v[32:47]
	s_nop 3
	ds_read_b128 v[156:159], v211 offset:0
	ds_read_b128 v[148:151], v211 offset:32
	ds_read_b128 v[152:155], v211 offset:8704
	ds_read_b128 v[144:147], v211 offset:8736
	ds_read_b128 v[140:143], v211 offset:64
	ds_read_b128 v[136:139], v211 offset:8768
	ds_read_b128 v[132:135], v211 offset:96
	ds_read_b128 v[128:131], v211 offset:8800
	v_exp_f32_e32 v48, v48
	v_exp_f32_e32 v49, v49
	v_exp_f32_e32 v50, v50
	v_exp_f32_e32 v51, v51
	v_exp_f32_e32 v52, v52
	v_exp_f32_e32 v53, v53
	v_exp_f32_e32 v54, v54
	v_exp_f32_e32 v55, v55
	v_exp_f32_e32 v56, v56
	v_exp_f32_e32 v57, v57
	v_exp_f32_e32 v58, v58
	v_exp_f32_e32 v59, v59
	v_exp_f32_e32 v60, v60
	v_exp_f32_e32 v61, v61
	v_exp_f32_e32 v62, v62
	v_exp_f32_e32 v63, v63
	v_exp_f32_e32 v32, v32
	v_exp_f32_e32 v33, v33
	v_exp_f32_e32 v34, v34
	v_exp_f32_e32 v35, v35
	v_exp_f32_e32 v36, v36
	v_exp_f32_e32 v37, v37
	v_exp_f32_e32 v38, v38
	v_exp_f32_e32 v39, v39
	v_exp_f32_e32 v40, v40
	v_exp_f32_e32 v41, v41
	v_exp_f32_e32 v42, v42
	v_exp_f32_e32 v43, v43
	v_exp_f32_e32 v44, v44
	v_exp_f32_e32 v45, v45
	v_exp_f32_e32 v46, v46
	v_exp_f32_e32 v47, v47
	v_add_f32_e32 v195, v48, v49
	v_add_f32_e32 v195, v195, v50
	v_add_f32_e32 v195, v195, v51
	v_add_f32_e32 v195, v195, v52
	v_add_f32_e32 v195, v195, v53
	v_add_f32_e32 v195, v195, v54
	v_add_f32_e32 v195, v195, v55
	v_add_f32_e32 v195, v195, v56
	v_add_f32_e32 v195, v195, v57
	v_add_f32_e32 v195, v195, v58
	v_add_f32_e32 v195, v195, v59
	v_add_f32_e32 v195, v195, v60
	v_add_f32_e32 v195, v195, v61
	v_add_f32_e32 v195, v195, v62
	v_add_f32_e32 v195, v195, v63
	v_add_f32_e32 v195, v195, v32
	v_add_f32_e32 v195, v195, v33
	v_add_f32_e32 v195, v195, v34
	v_add_f32_e32 v195, v195, v35
	v_add_f32_e32 v195, v195, v36
	v_add_f32_e32 v195, v195, v37
	v_add_f32_e32 v195, v195, v38
	v_add_f32_e32 v195, v195, v39
	v_add_f32_e32 v195, v195, v40
	v_add_f32_e32 v195, v195, v41
	v_add_f32_e32 v195, v195, v42
	v_add_f32_e32 v195, v195, v43
	v_add_f32_e32 v195, v195, v44
	v_add_f32_e32 v195, v195, v45
	v_add_f32_e32 v195, v195, v46
	v_add_f32_e32 v195, v195, v47
	v_cmp_nle_f32_e32 vcc, v195, v167
	s_cbranch_vccnz .Lsc0_fb0
	v_add_f32_e32 v213, v213, v195
	v_cvt_pk_bf16_f32 v48, v48, v49
	v_cvt_pk_bf16_f32 v49, v50, v51
	v_cvt_pk_bf16_f32 v50, v52, v53
	v_cvt_pk_bf16_f32 v51, v54, v55
	v_cvt_pk_bf16_f32 v52, v56, v57
	v_cvt_pk_bf16_f32 v53, v58, v59
	v_cvt_pk_bf16_f32 v54, v60, v61
	v_cvt_pk_bf16_f32 v55, v62, v63
	v_cvt_pk_bf16_f32 v56, v32, v33
	v_cvt_pk_bf16_f32 v57, v34, v35
	v_cvt_pk_bf16_f32 v58, v36, v37
	v_cvt_pk_bf16_f32 v59, v38, v39
	v_cvt_pk_bf16_f32 v60, v40, v41
	v_cvt_pk_bf16_f32 v61, v42, v43
	v_cvt_pk_bf16_f32 v62, v44, v45
	v_cvt_pk_bf16_f32 v63, v46, v47
	s_waitcnt lgkmcnt(7)
	v_mfma_f32_32x32x16_bf16 v[16:31], v[156:159], v[48:51], v[16:31]
	s_waitcnt lgkmcnt(5)
	v_mfma_f32_32x32x16_bf16 v[0:15], v[152:155], v[48:51], v[0:15]
	s_nop 0
	v_mfma_f32_32x32x16_bf16 v[16:31], v[148:151], v[52:55], v[16:31]
	s_waitcnt lgkmcnt(4)
	v_mfma_f32_32x32x16_bf16 v[0:15], v[144:147], v[52:55], v[0:15]
	s_waitcnt lgkmcnt(3)
	v_mfma_f32_32x32x16_bf16 v[16:31], v[140:143], v[56:59], v[16:31]
	s_waitcnt lgkmcnt(2)
	v_mfma_f32_32x32x16_bf16 v[0:15], v[136:139], v[56:59], v[0:15]
	s_waitcnt lgkmcnt(1)
	s_nop 0
	v_mfma_f32_32x32x16_bf16 v[16:31], v[132:135], v[60:63], v[16:31]
	s_waitcnt lgkmcnt(0)
	v_mfma_f32_32x32x16_bf16 v[0:15], v[128:131], v[60:63], v[0:15]
	ds_read_b128 v[36:39], v210 offset:13312
	ds_read_b128 v[132:135], v210 offset:13344
	ds_read_b128 v[136:139], v210 offset:13376
	ds_read_b128 v[140:143], v210 offset:13408
	ds_read_b128 v[144:147], v210 offset:13440
	ds_read_b128 v[148:151], v210 offset:13472
	ds_read_b128 v[40:43], v210 offset:19968
	ds_read_b128 v[152:155], v210 offset:20000
	ds_read_b128 v[156:159], v210 offset:20032
	ds_read_b128 v[234:237], v210 offset:20064
	ds_read_b128 v[238:241], v210 offset:20096
	ds_read_b128 v[242:245], v210 offset:20128

; DI float fexp2(float x) { return __builtin_amdgcn_exp2f(x); }
; DI void phase_attn(const Params& p, int hf, bool skipctx, char* smem, int& rot) {
;     ...
;     auto compute = [&](int buf, int half) {
;       const char* sk = smem + buf * STG + half * 64 * KROW; const char* sv = smem + buf * STG + KB_ + half * 128;
;       f32x16 st[2]; st[0] = zero16(); st[1] = zero16();
;       {
;         bf16x8 kf[2][6];
; #pragma unroll
;         for (int kb = 0; kb < 2; ++kb)
; #pragma unroll
;           for (int ks = 0; ks < 6; ++ks) kf[kb][ks] = *(const bf16x8*)(sk + (kb * 32 + r) * KROW + (ks * 16 + h * 8) * 2);
;         __builtin_amdgcn_sched_barrier(0);
; #pragma unroll
;         for (int ks = 0; ks < 6; ++ks)
; #pragma unroll
;           for (int kb = 0; kb < 2; ++kb) st[kb] = MFMA(kf[kb][ks], qf[ks], st[kb]);
;         __builtin_amdgcn_sched_barrier(0);
;       }
;       bf16x8 vf[2][2][2];
; #pragma unroll
;       for (int kb = 0; kb < 2; ++kb)
; #pragma unroll
;         for (int s2 = 0; s2 < 2; ++s2)
; #pragma unroll
;           for (int dvb = 0; dvb < 2; ++dvb) {
;             const char* vp = sv + (dvb * 32 + r) * VROW + (kb * 32 + 16 * s2 + 4 * h) * 2;
;             const s16x4 lo = *(const s16x4*)vp, hi = *(const s16x4*)(vp + 16);
;             vf[kb][s2][dvb] = __builtin_shufflevector(lo, hi, 0, 1, 2, 3, 4, 5, 6, 7);
;           }
;       float mx = st[0][0];
; #pragma unroll
;       for (int i = 0; i < 16; ++i) { mx = fmaxf(mx, st[0][i]); mx = fmaxf(mx, st[1][i]); }
;       if (__any(mx > m_run + 8.f)) {
;         mx = fmaxf(mx, __shfl_xor(mx, 32));
;         const float m_new = fmaxf(m_run, mx);
;         const float alpha = fexp2(m_run - m_new);
;         m_run = m_new;
;         l_run *= alpha;
; #pragma unroll
;         for (int i = 0; i < 16; ++i) { o[0][i] *= alpha; o[1][i] *= alpha; }
;       }
;       float ps = 0.f;
; #pragma unroll
;       for (int kb = 0; kb < 2; ++kb)
; #pragma unroll
;         for (int i = 0; i < 16; ++i) { const float e = fexp2(st[kb][i] - m_run); st[kb][i] = e; ps += e; }
;       l_run += ps;
; #pragma unroll
;       for (int kb = 0; kb < 2; ++kb)
; #pragma unroll
;         for (int s2 = 0; s2 < 2; ++s2) {
;           const bf16x8 pb = pack8(st[kb][8 * s2 + 0], st[kb][8 * s2 + 1], st[kb][8 * s2 + 2], st[kb][8 * s2 + 3], st[kb][8 * s2 + 4], st[kb][8 * s2 + 5], st[kb][8 * s2 + 6], st[kb][8 * s2 + 7]);
; #pragma unroll
.Lsc0_mj1:
	s_waitcnt lgkmcnt(11)
	v_mfma_f32_32x32x16_bf16 v[48:63], v[32:35], v[64:67], v[176:191]
	s_waitcnt lgkmcnt(5)
	v_mfma_f32_32x32x16_bf16 v[32:47], v[36:39], v[64:67], v[176:191]
	v_mfma_f32_32x32x16_bf16 v[48:63], v[128:131], v[68:71], v[48:63]
	s_waitcnt lgkmcnt(4)
	v_mfma_f32_32x32x16_bf16 v[32:47], v[148:151], v[68:71], v[32:47]
	v_mfma_f32_32x32x16_bf16 v[48:63], v[132:135], v[72:75], v[48:63]
	s_waitcnt lgkmcnt(3)
	v_mfma_f32_32x32x16_bf16 v[32:47], v[152:155], v[72:75], v[32:47]
	v_mfma_f32_32x32x16_bf16 v[48:63], v[136:139], v[88:91], v[48:63]
	s_waitcnt lgkmcnt(2)
	v_mfma_f32_32x32x16_bf16 v[32:47], v[156:159], v[88:91], v[32:47]
	v_mfma_f32_32x32x16_bf16 v[48:63], v[140:143], v[96:99], v[48:63]
	s_waitcnt lgkmcnt(1)
	v_mfma_f32_32x32x16_bf16 v[32:47], v[214:217], v[96:99], v[32:47]
	v_mfma_f32_32x32x16_bf16 v[48:63], v[144:147], v[100:103], v[48:63]
	s_waitcnt lgkmcnt(0)
	v_mfma_f32_32x32x16_bf16 v[32:47], v[234:237], v[100:103], v[32:47]
	s_nop 3
	ds_read_b128 v[152:155], v211 offset:52736
	ds_read_b128 v[156:159], v211 offset:44032
	ds_read_b128 v[148:151], v211 offset:44064
	ds_read_b128 v[144:147], v211 offset:52768
	ds_read_b128 v[140:143], v211 offset:44096
	ds_read_b128 v[136:139], v211 offset:52800
	ds_read_b128 v[132:135], v211 offset:44128
	ds_read_b128 v[128:131], v211 offset:52832
	v_exp_f32_e32 v48, v48
	v_exp_f32_e32 v49, v49
	v_exp_f32_e32 v50, v50
	v_exp_f32_e32 v51, v51
	v_exp_f32_e32 v52, v52
	v_exp_f32_e32 v53, v53
	v_exp_f32_e32 v54, v54
	v_exp_f32_e32 v55, v55
	v_exp_f32_e32 v56, v56
	v_exp_f32_e32 v57, v57
	v_exp_f32_e32 v58, v58
	v_exp_f32_e32 v59, v59
	v_exp_f32_e32 v60, v60
	v_exp_f32_e32 v61, v61
	v_exp_f32_e32 v62, v62
	v_exp_f32_e32 v63, v63
	v_exp_f32_e32 v32, v32
	v_exp_f32_e32 v33, v33
	v_exp_f32_e32 v34, v34
	v_exp_f32_e32 v35, v35
	v_exp_f32_e32 v36, v36
	v_exp_f32_e32 v37, v37
	v_exp_f32_e32 v38, v38
	v_exp_f32_e32 v39, v39
	v_exp_f32_e32 v40, v40
	v_exp_f32_e32 v41, v41
	v_exp_f32_e32 v42, v42
	v_exp_f32_e32 v43, v43
	v_exp_f32_e32 v44, v44
	v_exp_f32_e32 v45, v45
	v_exp_f32_e32 v46, v46
	v_exp_f32_e32 v47, v47
	v_add_f32_e32 v195, v48, v49
	v_add_f32_e32 v195, v195, v50
	v_add_f32_e32 v195, v195, v51
	v_add_f32_e32 v195, v195, v52
	v_add_f32_e32 v195, v195, v53
	v_add_f32_e32 v195, v195, v54
	v_add_f32_e32 v195, v195, v55
	v_add_f32_e32 v195, v195, v56
	v_add_f32_e32 v195, v195, v57
	v_add_f32_e32 v195, v195, v58
	v_add_f32_e32 v195, v195, v59
	v_add_f32_e32 v195, v195, v60
	v_add_f32_e32 v195, v195, v61
	v_add_f32_e32 v195, v195, v62
	v_add_f32_e32 v195, v195, v63
	v_add_f32_e32 v195, v195, v32
	v_add_f32_e32 v195, v195, v33
	v_add_f32_e32 v195, v195, v34
	v_add_f32_e32 v195, v195, v35
	v_add_f32_e32 v195, v195, v36
	v_add_f32_e32 v195, v195, v37
	v_add_f32_e32 v195, v195, v38
	v_add_f32_e32 v195, v195, v39
	v_add_f32_e32 v195, v195, v40
	v_add_f32_e32 v195, v195, v41
	v_add_f32_e32 v195, v195, v42
	v_add_f32_e32 v195, v195, v43
	v_add_f32_e32 v195, v195, v44
	v_add_f32_e32 v195, v195, v45
	v_add_f32_e32 v195, v195, v46
	v_add_f32_e32 v195, v195, v47
	v_cmp_nle_f32_e32 vcc, v195, v167
	s_cbranch_vccnz .Lsc0_fb2
	v_add_f32_e32 v213, v213, v195
	v_cvt_pk_bf16_f32 v48, v48, v49
	v_cvt_pk_bf16_f32 v49, v50, v51
	v_cvt_pk_bf16_f32 v50, v52, v53
	v_cvt_pk_bf16_f32 v51, v54, v55
	v_cvt_pk_bf16_f32 v52, v56, v57
	v_cvt_pk_bf16_f32 v53, v58, v59
	v_cvt_pk_bf16_f32 v54, v60, v61
	v_cvt_pk_bf16_f32 v55, v62, v63
	v_cvt_pk_bf16_f32 v56, v32, v33
	v_cvt_pk_bf16_f32 v57, v34, v35
	v_cvt_pk_bf16_f32 v58, v36, v37
	v_cvt_pk_bf16_f32 v59, v38, v39
	v_cvt_pk_bf16_f32 v60, v40, v41
	v_cvt_pk_bf16_f32 v61, v42, v43
	v_cvt_pk_bf16_f32 v62, v44, v45
	v_cvt_pk_bf16_f32 v63, v46, v47
	s_waitcnt lgkmcnt(6)
	v_mfma_f32_32x32x16_bf16 v[16:31], v[156:159], v[48:51], v[16:31]
	v_mfma_f32_32x32x16_bf16 v[0:15], v[152:155], v[48:51], v[0:15]
	s_waitcnt lgkmcnt(5)
	v_mfma_f32_32x32x16_bf16 v[16:31], v[148:151], v[52:55], v[16:31]
	s_waitcnt lgkmcnt(4)
	v_mfma_f32_32x32x16_bf16 v[0:15], v[144:147], v[52:55], v[0:15]
	s_waitcnt lgkmcnt(3)
	v_mfma_f32_32x32x16_bf16 v[16:31], v[140:143], v[56:59], v[16:31]
	s_waitcnt lgkmcnt(2)
	v_mfma_f32_32x32x16_bf16 v[0:15], v[136:139], v[56:59], v[0:15]
	s_waitcnt lgkmcnt(1)
	s_nop 0
	v_mfma_f32_32x32x16_bf16 v[16:31], v[132:135], v[60:63], v[16:31]
	s_waitcnt lgkmcnt(0)
	v_mfma_f32_32x32x16_bf16 v[0:15], v[128:131], v[60:63], v[0:15]
	ds_read_b128 v[36:39], v210 offset:57344
	ds_read_b128 v[132:135], v210 offset:57376
	ds_read_b128 v[136:139], v210 offset:57408
	ds_read_b128 v[140:143], v210 offset:57440
	ds_read_b128 v[144:147], v210 offset:57472
	ds_read_b128 v[148:151], v210 offset:57504
	ds_read_b128 v[40:43], v210 offset:64000
	ds_read_b128 v[152:155], v210 offset:64032
	ds_read_b128 v[156:159], v210 offset:64064
	ds_read_b128 v[216:219], v210 offset:64096
	ds_read_b128 v[234:237], v210 offset:64128
	ds_read_b128 v[238:241], v210 offset:64160
